# speedup vs baseline: 1.0035x; 1.0000x over previous
; __device__ __forceinline__ unsigned xb_ld(unsigned* p)              { return __hip_atomic_load(p, __ATOMIC_RELAXED, __HIP_MEMORY_SCOPE_AGENT); }
; __device__ __forceinline__ void xcd_barrier_complete(unsigned* bar, unsigned x, unsigned& nloc, unsigned& nx) {
;     ...
;     for (;;) {
;         sum = 0u; cnt = 0u; mine = 0u;
; #pragma unroll
;         for (unsigned j = 0; j < 16; ++j) { const unsigned c = xb_ld(&bar[XB_XCNT(j)]); sum += c; cnt += (c > 0u) ? 1u : 0u; mine = (j == x) ? c : mine; }
;         if (sum == G) break;
;         __builtin_amdgcn_s_sleep(1);
;         if ((++sp & 255u) == 0u) { if (xb_ld(&bar[XB_TMO])) break; if (sp > XB_SPIN_CAP) { atomicAdd(&bar[XB_TMO], 1u); break; } }
;     }
.LBB0_108:
	v_readlane_b32 s22, v252, 46
	v_readlane_b32 s23, v252, 47
	s_mov_b64 s[28:29], -1
	s_waitcnt lgkmcnt(0)
	s_nop 2
	global_load_dword v0, v65, s[22:23] sc1
	v_readlane_b32 s22, v252, 48
	v_readlane_b32 s23, v252, 49
	s_nop 4
	global_load_dword v1, v65, s[22:23] sc1
	v_readlane_b32 s22, v252, 50
	v_readlane_b32 s23, v252, 51
	s_nop 0
	s_nop 0
	s_nop 2
	global_load_dword v2, v65, s[22:23] sc1
	v_readlane_b32 s22, v252, 52
	v_readlane_b32 s23, v252, 53
	s_nop 0
	s_nop 0
	s_nop 2
	global_load_dword v3, v65, s[22:23] sc1
	v_readlane_b32 s22, v252, 54
	v_readlane_b32 s23, v252, 55
	s_nop 0
	s_nop 0
	s_nop 2
	global_load_dword v4, v65, s[22:23] sc1
	v_readlane_b32 s22, v252, 56
	v_readlane_b32 s23, v252, 57
	s_nop 0
	s_nop 0
	s_nop 2
	global_load_dword v5, v65, s[22:23] sc1
	v_readlane_b32 s22, v252, 58
	v_readlane_b32 s23, v252, 59
	s_nop 0
	s_nop 0
	s_nop 2
	global_load_dword v6, v65, s[22:23] sc1
	v_readlane_b32 s22, v252, 60
	v_readlane_b32 s23, v252, 61
	s_nop 0
	s_nop 0
	s_nop 2
	global_load_dword v7, v65, s[22:23] sc1
	v_readlane_b32 s22, v252, 62
	v_readlane_b32 s23, v252, 63
	s_nop 0
	s_nop 0
	s_nop 2
	global_load_dword v8, v65, s[22:23] sc1
	v_readlane_b32 s22, v253, 0
	v_readlane_b32 s23, v253, 1
	s_nop 0
	s_nop 0
	s_nop 2
	global_load_dword v9, v65, s[22:23] sc1
	v_readlane_b32 s22, v253, 2
	v_readlane_b32 s23, v253, 3
	s_nop 0
	s_nop 0
	s_nop 2
	global_load_dword v10, v65, s[22:23] sc1
	v_readlane_b32 s22, v253, 4
	v_readlane_b32 s23, v253, 5
	s_nop 0
	s_nop 0
	s_nop 2
	global_load_dword v11, v65, s[22:23] sc1
	v_readlane_b32 s22, v253, 6
	v_readlane_b32 s23, v253, 7
	s_nop 0
	s_nop 0
	s_nop 2
	global_load_dword v12, v65, s[22:23] sc1
	v_readlane_b32 s22, v253, 8
	v_readlane_b32 s23, v253, 9
	s_nop 0
	s_nop 0
	s_nop 2
	global_load_dword v13, v65, s[22:23] sc1
	v_readlane_b32 s22, v253, 10
	v_readlane_b32 s23, v253, 11
	s_nop 0
	s_nop 0
	s_nop 2
	global_load_dword v14, v65, s[22:23] sc1
	v_readlane_b32 s22, v253, 12
	v_readlane_b32 s23, v253, 13
	s_nop 0
	s_nop 0
	s_nop 2
	global_load_dword v15, v65, s[22:23] sc1
	s_mov_b64 s[22:23], -1
	s_waitcnt vmcnt(0)
	v_add_u32_e32 v16, v1, v0
	v_add_u32_e32 v16, v16, v2
	v_add_u32_e32 v16, v16, v3
	v_add_u32_e32 v16, v16, v4
	v_add_u32_e32 v16, v16, v5
	v_add_u32_e32 v16, v16, v6
	v_add_u32_e32 v16, v16, v7
	v_add_u32_e32 v16, v16, v8
	v_add_u32_e32 v16, v16, v9
	v_add_u32_e32 v16, v16, v10
	v_add_u32_e32 v16, v16, v11
	v_add_u32_e32 v16, v16, v12
	v_add_u32_e32 v16, v16, v13
	v_add_u32_e32 v16, v16, v14
	v_add_u32_e32 v16, v16, v15
	v_cmp_eq_u32_e32 vcc, s19, v16
	s_cbranch_vccnz .LBB0_107
	s_and_b32 s3, s2, 0xff
	s_cmp_eq_u32 s3, 0
	s_mov_b64 s[36:37], -1
	s_sleep 1
	s_cbranch_scc0 .LBB0_112
	v_readlane_b32 s22, v252, 44
	v_readlane_b32 s23, v252, 45
	s_nop 4
	global_load_dword v16, v65, s[22:23] sc1
	s_waitcnt vmcnt(0)
	v_cmp_eq_u32_e32 vcc, 0, v16
	s_cbranch_vccnz .LBB0_114
	s_mov_b64 s[36:37], 0
	s_mov_b64 s[22:23], -1
